# B5 + XCD leaders issue their acquire buffer_inv right behind buffer_wbl2 (before arriving at the top counter); no post-release invalidate left
# speedup vs baseline: 1.0038x; 1.0038x over previous
; __device__ __forceinline__ unsigned xb_ld(unsigned* p)              { return __hip_atomic_load(p, __ATOMIC_RELAXED, __HIP_MEMORY_SCOPE_AGENT); }
; __device__ __forceinline__ unsigned xb_add(unsigned* p, unsigned v) { return __hip_atomic_fetch_add(p, v, __ATOMIC_RELAXED, __HIP_MEMORY_SCOPE_AGENT); }
; #define XB_SPIN(cond, bar) do { unsigned _sp = 0; while (cond) { __builtin_amdgcn_s_sleep(1); \
;     if ((++_sp & 255u) == 0u) { if (xb_ld(&(bar)[XB_TMO])) break; if (_sp > XB_SPIN_CAP) { atomicAdd(&(bar)[XB_TMO], 1u); break; } } } } while (0)
; __device__ __forceinline__ void xcd_barrier(const XcdBarrier& b, int tid) {
;     ...
;         if (old + 1u == (gen + 1u) * nloc) {
;             __builtin_amdgcn_fence(__ATOMIC_RELEASE, "agent");
;             asm volatile("s_waitcnt vmcnt(0)" ::: "memory");
;             const unsigned og = xb_add(&bar[XB_TOP], 1u);
;             const unsigned tg = og / nx;
;             if (og + 1u == (tg + 1u) * nx) xb_add(&bar[XB_TOPGEN], 1u);
;             else XB_SPIN(xb_ld(&bar[XB_TOPGEN]) == tg, bar);
;             __builtin_amdgcn_fence(__ATOMIC_ACQUIRE, "agent");
;             xb_add(&bar[XB_XGEN(b.x)], 1u);
;             asm volatile("s_waitcnt vmcnt(0)" ::: "memory");
.LBB0_76:
	s_andn2_saveexec_b64 s[4:5], s[4:5]
	s_cbranch_execz .LBB0_94
	s_mov_b64 s[4:5], exec
	buffer_wbl2 sc1
	buffer_inv sc1
	s_waitcnt lgkmcnt(0)
	s_waitcnt vmcnt(0)
	v_mbcnt_lo_u32_b32 v1, s4, 0
	v_mbcnt_hi_u32_b32 v1, s5, v1
	v_cmp_eq_u32_e32 vcc, 0, v1
	s_and_saveexec_b64 s[6:7], vcc
	s_cbranch_execz .LBB0_79
	s_bcnt1_i32_b64 s4, s[4:5]
	v_mov_b32_e32 v2, 0x7000
	v_mov_b32_e32 v3, s4
	global_atomic_add v2, v2, v3, s[82:83] offset:1024 sc0

; __device__ __forceinline__ unsigned xb_ld(unsigned* p)              { return __hip_atomic_load(p, __ATOMIC_RELAXED, __HIP_MEMORY_SCOPE_AGENT); }
; __device__ __forceinline__ unsigned xb_add(unsigned* p, unsigned v) { return __hip_atomic_fetch_add(p, v, __ATOMIC_RELAXED, __HIP_MEMORY_SCOPE_AGENT); }
; #define XB_SPIN(cond, bar) do { unsigned _sp = 0; while (cond) { __builtin_amdgcn_s_sleep(1); \
;     if ((++_sp & 255u) == 0u) { if (xb_ld(&(bar)[XB_TMO])) break; if (_sp > XB_SPIN_CAP) { atomicAdd(&(bar)[XB_TMO], 1u); break; } } } } while (0)
; __device__ __forceinline__ void xcd_barrier(const XcdBarrier& b, int tid) {
;     ...
;         if (old + 1u == (gen + 1u) * nloc) {
;             __builtin_amdgcn_fence(__ATOMIC_RELEASE, "agent");
;             asm volatile("s_waitcnt vmcnt(0)" ::: "memory");
;             const unsigned og = xb_add(&bar[XB_TOP], 1u);
;             const unsigned tg = og / nx;
;             if (og + 1u == (tg + 1u) * nx) xb_add(&bar[XB_TOPGEN], 1u);
;             else XB_SPIN(xb_ld(&bar[XB_TOPGEN]) == tg, bar);
;             __builtin_amdgcn_fence(__ATOMIC_ACQUIRE, "agent");
;             xb_add(&bar[XB_XGEN(b.x)], 1u);
;             asm volatile("s_waitcnt vmcnt(0)" ::: "memory");
.LBB0_190:
	s_andn2_saveexec_b64 s[2:3], s[2:3]
	s_cbranch_execz .LBB0_208
	s_mov_b64 s[2:3], exec
	buffer_wbl2 sc1
	buffer_inv sc1
	s_waitcnt lgkmcnt(0)
	s_waitcnt vmcnt(0)
	v_mbcnt_lo_u32_b32 v1, s2, 0
	v_mbcnt_hi_u32_b32 v1, s3, v1
	v_cmp_eq_u32_e32 vcc, 0, v1
	s_and_saveexec_b64 s[4:5], vcc
	s_cbranch_execz .LBB0_193
	s_bcnt1_i32_b64 s2, s[2:3]
	v_mov_b32_e32 v2, s2
	v_readlane_b32 s2, v254, 11
	v_readlane_b32 s3, v254, 12
	s_nop 4
	global_atomic_add v2, v161, v2, s[2:3] sc0

; __device__ __forceinline__ unsigned xb_ld(unsigned* p)              { return __hip_atomic_load(p, __ATOMIC_RELAXED, __HIP_MEMORY_SCOPE_AGENT); }
; __device__ __forceinline__ unsigned xb_add(unsigned* p, unsigned v) { return __hip_atomic_fetch_add(p, v, __ATOMIC_RELAXED, __HIP_MEMORY_SCOPE_AGENT); }
; #define XB_SPIN(cond, bar) do { unsigned _sp = 0; while (cond) { __builtin_amdgcn_s_sleep(1); \
;     if ((++_sp & 255u) == 0u) { if (xb_ld(&(bar)[XB_TMO])) break; if (_sp > XB_SPIN_CAP) { atomicAdd(&(bar)[XB_TMO], 1u); break; } } } } while (0)
; __device__ __forceinline__ void xcd_barrier(const XcdBarrier& b, int tid) {
;     ...
;         if (old + 1u == (gen + 1u) * nloc) {
;             __builtin_amdgcn_fence(__ATOMIC_RELEASE, "agent");
;             asm volatile("s_waitcnt vmcnt(0)" ::: "memory");
;             const unsigned og = xb_add(&bar[XB_TOP], 1u);
;             const unsigned tg = og / nx;
;             if (og + 1u == (tg + 1u) * nx) xb_add(&bar[XB_TOPGEN], 1u);
;             else XB_SPIN(xb_ld(&bar[XB_TOPGEN]) == tg, bar);
;             __builtin_amdgcn_fence(__ATOMIC_ACQUIRE, "agent");
;             xb_add(&bar[XB_XGEN(b.x)], 1u);
;             asm volatile("s_waitcnt vmcnt(0)" ::: "memory");
.LBB0_1516:
	s_andn2_saveexec_b64 s[0:1], s[4:5]
	s_cbranch_execz .LBB0_1534
	s_mov_b64 s[4:5], exec
	buffer_wbl2 sc1
	buffer_inv sc1
	s_waitcnt lgkmcnt(0)
	s_waitcnt vmcnt(0)
	v_mbcnt_lo_u32_b32 v1, s4, 0
	v_mbcnt_hi_u32_b32 v1, s5, v1
	v_cmp_eq_u32_e32 vcc, 0, v1
	s_and_saveexec_b64 s[6:7], vcc
	s_cbranch_execz .LBB0_1519
	s_bcnt1_i32_b64 s0, s[4:5]
	v_mov_b32_e32 v2, s0
	v_readlane_b32 s0, v254, 11
	v_readlane_b32 s1, v254, 12
	s_nop 4
	global_atomic_add v2, v161, v2, s[0:1] sc0

; __device__ __forceinline__ unsigned xb_ld(unsigned* p)              { return __hip_atomic_load(p, __ATOMIC_RELAXED, __HIP_MEMORY_SCOPE_AGENT); }
; __device__ __forceinline__ unsigned xb_add(unsigned* p, unsigned v) { return __hip_atomic_fetch_add(p, v, __ATOMIC_RELAXED, __HIP_MEMORY_SCOPE_AGENT); }
; #define XB_SPIN(cond, bar) do { unsigned _sp = 0; while (cond) { __builtin_amdgcn_s_sleep(1); \
;     if ((++_sp & 255u) == 0u) { if (xb_ld(&(bar)[XB_TMO])) break; if (_sp > XB_SPIN_CAP) { atomicAdd(&(bar)[XB_TMO], 1u); break; } } } } while (0)
; __device__ __forceinline__ void xcd_barrier(const XcdBarrier& b, int tid) {
;     ...
;         if (old + 1u == (gen + 1u) * nloc) {
;             __builtin_amdgcn_fence(__ATOMIC_RELEASE, "agent");
;             asm volatile("s_waitcnt vmcnt(0)" ::: "memory");
;             const unsigned og = xb_add(&bar[XB_TOP], 1u);
;             const unsigned tg = og / nx;
;             if (og + 1u == (tg + 1u) * nx) xb_add(&bar[XB_TOPGEN], 1u);
;             else XB_SPIN(xb_ld(&bar[XB_TOPGEN]) == tg, bar);
;             __builtin_amdgcn_fence(__ATOMIC_ACQUIRE, "agent");
;             xb_add(&bar[XB_XGEN(b.x)], 1u);
;             asm volatile("s_waitcnt vmcnt(0)" ::: "memory");
.LBB0_1840:
	s_andn2_saveexec_b64 s[2:3], s[2:3]
	s_cbranch_execz .LBB0_1858
	s_mov_b64 s[2:3], exec
	buffer_wbl2 sc1
	buffer_inv sc1
	s_waitcnt lgkmcnt(0)
	s_waitcnt vmcnt(0)
	v_mbcnt_lo_u32_b32 v1, s2, 0
	v_mbcnt_hi_u32_b32 v1, s3, v1
	v_cmp_eq_u32_e32 vcc, 0, v1
	s_and_saveexec_b64 s[4:5], vcc
	s_cbranch_execz .LBB0_1843
	s_bcnt1_i32_b64 s2, s[2:3]
	v_mov_b32_e32 v3, s2
	v_readlane_b32 s2, v254, 11
	v_mov_b32_e32 v2, 0
	v_readlane_b32 s3, v254, 12
	s_nop 4
	global_atomic_add v2, v2, v3, s[2:3] sc0
